# p2b start: the relative-position-bias table copy (3-4 entries per thread) issues all its loads at once instead of 2 serialized load-wait rounds
# baseline (speedup 1.0000x reference)
.LBB0_666:
	s_cmp_le_i32 s78, s0
	s_cselect_b64 s[12:13], -1, 0
	s_and_b64 s[0:1], s[12:13], s[18:19]
	s_andn2_b64 vcc, exec, s[0:1]
	s_cbranch_vccnz .LBB0_728
	v_mov_b32_e32 v193, v233
	s_mov_b32 s24, s2
	v_mov_b32_e32 v152, v232
	s_mov_b32 s25, s71
	s_mov_b32 s5, s3
	s_movk_i32 s0, 0x744
	s_mov_b64 s[14:15], 0
	v_cmp_gt_i32_e32 vcc, s0, v152
	s_and_saveexec_b64 s[16:17], vcc
	s_cbranch_execz .LBB0_680
	s_mul_i32 s26, s4, 0x744
	v_readlane_b32 s54, v254, 16
	v_readlane_b32 s55, v254, 17
	s_lshl_b64 s[0:1], s[26:27], 2
	v_lshlrev_b32_e32 v2, 2, v152
	s_waitcnt vmcnt(0)
	s_add_u32 s38, s54, s0
	s_addc_u32 s39, s55, s1
	v_readlane_b32 s0, v255, 19
	v_add_u32_e32 v3, 0x1000, v2
	v_cmp_gt_u32_e32 vcc, 0x144, v152
	global_load_dword v4, v2, s[38:39]
	global_load_dword v5, v2, s[38:39] offset:2048
	global_load_dword v6, v3, s[38:39]
	s_and_saveexec_b64 s[40:41], vcc
	global_load_dword v7, v3, s[38:39] offset:2048
	s_or_b64 exec, exec, s[40:41]
	v_add_u32_e32 v8, s0, v2
	s_waitcnt vmcnt(0)
	v_mul_f32_e32 v4, 0x3fb8aa3b, v4
	v_mul_f32_e32 v5, 0x3fb8aa3b, v5
	v_mul_f32_e32 v6, 0x3fb8aa3b, v6
	v_mul_f32_e32 v7, 0x3fb8aa3b, v7
	ds_write_b32 v8, v4
	ds_write_b32 v8, v5 offset:2048
	ds_write_b32 v8, v6 offset:4096
	s_and_saveexec_b64 s[40:41], vcc
	ds_write_b32 v8, v7 offset:6144
	s_or_b64 exec, exec, s[40:41]
